# speedup vs baseline: 1.0262x; 1.0262x over previous
; __device__ __forceinline__ float siluf_(float x) { return x * sigmoidf_(x); }
; __device__ __forceinline__ u32x2 pack4(float a, float b, float c, float d) { return u32x2{cvtpk(a, b), cvtpk(c, d)}; }
; __device__ __forceinline__ u32x2 pack4(const f32x4& v) { return u32x2{cvtpk(v[0], v[1]), cvtpk(v[2], v[3])}; }
; #define SBAR() __builtin_amdgcn_sched_barrier(0)
; __global__ void __launch_bounds__(512) fwd_megakernel(Params p) {
;     ...
;         #pragma unroll
;         for (int ai = 0; ai < 2; ++ai)
;           #pragma unroll
;           for (int m = 0; m < 4; ++m) { SBAR();
;             int row = brow + ai * 128 + wr * 64 + m * 16 + fr;
;             const float rs = xl[ai * 128 + wr * 64 + m * 16 + fr];
;             bf16* ad = p_act + (long)row * DFF + pn * 128 + wc * 32 + fq * 4;
;             #pragma unroll
;             for (int n = 0; n < 2; ++n) {
;               float a[4];
;               #pragma unroll
;               for (int j = 0; j < 4; ++j) { float g = acc[ai][0][m][n][j] * rs, u = acc[ai][1][m][n][j] * rs; a[j] = siluf_(g) * u; }
;               *reinterpret_cast<u32x2*>(ad + n * 16) = pack4(a[0], a[1], a[2], a[3]);
;             }
.LBB0_664:
	v_mov_b32_e32 v132, v252
	s_waitcnt lgkmcnt(0)
	s_barrier
	s_nop 0
	v_ashrrev_i32_e32 v1, 2, v132
	v_and_b32_e32 v0, 15, v132
	v_and_b32_e32 v1, 0xffffffc0, v1
	v_or_b32_e32 v2, v1, v0
	v_lshlrev_b32_e32 v1, 2, v1
	v_lshlrev_b32_e32 v0, 2, v0
	v_add3_u32 v134, s77, v1, v0
	ds_read_b32 v136, v134
	ds_read_b32 v137, v134 offset:64
	ds_read_b32 v138, v134 offset:128
	ds_read_b32 v139, v134 offset:192
	ds_read_b32 v142, v134 offset:512
	ds_read_b32 v143, v134 offset:576
	ds_read_b32 v145, v134 offset:640
	v_add_u32_e32 v135, s30, v2
	v_mov_b64_e32 v[0:1], s[34:35]
	s_lshl_b32 s4, s63, 7
	s_ashr_i32 s5, s4, 31
	s_lshl_b64 s[4:5], s[4:5], 1
	v_mad_i64_i32 v[2:3], vcc, v135, s61, v[0:1]
	v_lshlrev_b32_e32 v0, 1, v132
	v_lshrrev_b32_e32 v1, 1, v132
	v_and_b32_e32 v0, 32, v0
	v_and_b32_e32 v1, 16, v1
	v_and_b32_e32 v132, 0xc0, v132
	v_or_b32_e32 v0, v0, v1
	v_lshl_add_u64 v[2:3], v[2:3], 0, s[4:5]
	v_or_b32_e32 v132, v132, v0
	s_mov_b32 s30, 0x16000
	s_mov_b32 s31, 0
	s_mov_b64 s[38:39], -1
	v_lshl_add_u64 v[2:3], v[2:3], 0, v[132:133]
	ds_read_b32 v132, v134 offset:704
	s_waitcnt lgkmcnt(0)
	v_mul_f32_e32 v1, v136, v136
	v_mul_f32_e32 v0, 0xbfb8aa3b, v136
	v_rcp_f32_e32 v1, v1
	v_mul_f32_e32 v128, v124, v128
	v_mul_f32_e32 v129, v125, v129
	v_mul_f32_e32 v130, v126, v130
	v_mul_f32_e32 v131, v127, v131
	v_mul_f32_e32 v124, v0, v124
	v_mul_f32_e32 v125, v0, v125
	v_mul_f32_e32 v126, v0, v126
	v_mul_f32_e32 v127, v0, v127
	v_exp_f32_e32 v124, v124
	v_exp_f32_e32 v125, v125
	v_exp_f32_e32 v126, v126
	v_exp_f32_e32 v127, v127
	v_fma_f32 v124, v124, v1, v1
	v_fma_f32 v125, v125, v1, v1
	v_fma_f32 v126, v126, v1, v1
	v_fma_f32 v127, v127, v1, v1
	v_rcp_f32_e32 v124, v124
	v_rcp_f32_e32 v125, v125
	v_rcp_f32_e32 v126, v126
	v_rcp_f32_e32 v127, v127
	v_mul_f32_e32 v128, v128, v124
	v_mul_f32_e32 v129, v129, v125
	v_mul_f32_e32 v130, v130, v126
	v_mul_f32_e32 v131, v131, v127
	v_mul_f32_e32 v120, v116, v120
	v_mul_f32_e32 v121, v117, v121
	v_mul_f32_e32 v122, v118, v122
	v_mul_f32_e32 v123, v119, v123
	v_mul_f32_e32 v116, v0, v116
	v_mul_f32_e32 v117, v0, v117
	v_mul_f32_e32 v118, v0, v118
	v_mul_f32_e32 v119, v0, v119
	v_exp_f32_e32 v116, v116
	v_exp_f32_e32 v117, v117
	v_exp_f32_e32 v118, v118
	v_exp_f32_e32 v119, v119
	v_fma_f32 v116, v116, v1, v1
	v_fma_f32 v117, v117, v1, v1
	v_fma_f32 v118, v118, v1, v1
	v_fma_f32 v119, v119, v1, v1
	v_rcp_f32_e32 v116, v116
	v_rcp_f32_e32 v117, v117
	v_rcp_f32_e32 v118, v118
	v_rcp_f32_e32 v119, v119
	v_mul_f32_e32 v120, v120, v116
	v_mul_f32_e32 v121, v121, v117
	v_mul_f32_e32 v122, v122, v118
	v_mul_f32_e32 v123, v123, v119
	v_cvt_pk_bf16_f32 v124, v128, v129
	v_cvt_pk_bf16_f32 v125, v130, v131
	v_cvt_pk_bf16_f32 v126, v120, v121
	v_cvt_pk_bf16_f32 v127, v122, v123
	s_nop 1
	v_permlane16_swap_b32_e32 v124, v126
	v_permlane16_swap_b32_e32 v125, v127
	global_store_dwordx4 v[2:3], v[124:127], off
	v_lshl_add_u64 v[134:135], v[2:3], 0, s[30:31]
	v_mul_f32_e32 v1, v137, v137
	v_mul_f32_e32 v0, 0xbfb8aa3b, v137
	v_rcp_f32_e32 v1, v1
	v_mul_f32_e32 v112, v108, v112
	v_mul_f32_e32 v113, v109, v113
	v_mul_f32_e32 v114, v110, v114
	v_mul_f32_e32 v115, v111, v115
	v_mul_f32_e32 v108, v0, v108
	v_mul_f32_e32 v109, v0, v109
	v_mul_f32_e32 v110, v0, v110
	v_mul_f32_e32 v111, v0, v111
	v_exp_f32_e32 v108, v108
	v_exp_f32_e32 v109, v109
	v_exp_f32_e32 v110, v110
	v_exp_f32_e32 v111, v111
	v_fma_f32 v108, v108, v1, v1
	v_fma_f32 v109, v109, v1, v1
	v_fma_f32 v110, v110, v1, v1
	v_fma_f32 v111, v111, v1, v1
	v_rcp_f32_e32 v108, v108
	v_rcp_f32_e32 v109, v109
	v_rcp_f32_e32 v110, v110
	v_rcp_f32_e32 v111, v111
	v_mul_f32_e32 v112, v112, v108
	v_mul_f32_e32 v113, v113, v109
	v_mul_f32_e32 v114, v114, v110
	v_mul_f32_e32 v115, v115, v111
	v_mul_f32_e32 v104, v100, v104
	v_mul_f32_e32 v105, v101, v105
	v_mul_f32_e32 v106, v102, v106
	v_mul_f32_e32 v107, v103, v107
	v_mul_f32_e32 v100, v0, v100
	v_mul_f32_e32 v101, v0, v101
	v_mul_f32_e32 v102, v0, v102
	v_mul_f32_e32 v103, v0, v103
	v_exp_f32_e32 v100, v100
	v_exp_f32_e32 v101, v101
	v_exp_f32_e32 v102, v102
	v_exp_f32_e32 v103, v103
	v_fma_f32 v100, v100, v1, v1
	v_fma_f32 v101, v101, v1, v1
	v_fma_f32 v102, v102, v1, v1
	v_fma_f32 v103, v103, v1, v1
	v_rcp_f32_e32 v100, v100
	v_rcp_f32_e32 v101, v101
	v_rcp_f32_e32 v102, v102
	v_rcp_f32_e32 v103, v103
	v_mul_f32_e32 v104, v104, v100
	v_mul_f32_e32 v105, v105, v101
	v_mul_f32_e32 v106, v106, v102
	v_mul_f32_e32 v107, v107, v103
	v_cvt_pk_bf16_f32 v108, v112, v113
	v_cvt_pk_bf16_f32 v109, v114, v115
	v_cvt_pk_bf16_f32 v110, v104, v105
	v_cvt_pk_bf16_f32 v111, v106, v107
	s_nop 1
	v_permlane16_swap_b32_e32 v108, v110
	v_permlane16_swap_b32_e32 v109, v111
	global_store_dwordx4 v[134:135], v[108:111], off
	v_lshl_add_u64 v[2:3], v[134:135], 0, s[30:31]
	v_mul_f32_e32 v1, v138, v138
	v_mul_f32_e32 v0, 0xbfb8aa3b, v138
	v_rcp_f32_e32 v1, v1
	v_mul_f32_e32 v96, v92, v96
	v_mul_f32_e32 v97, v93, v97
	v_mul_f32_e32 v98, v94, v98
	v_mul_f32_e32 v99, v95, v99
	v_mul_f32_e32 v92, v0, v92
	v_mul_f32_e32 v93, v0, v93
	v_mul_f32_e32 v94, v0, v94
	v_mul_f32_e32 v95, v0, v95
	v_exp_f32_e32 v92, v92
	v_exp_f32_e32 v93, v93
	v_exp_f32_e32 v94, v94
	v_exp_f32_e32 v95, v95
	v_fma_f32 v92, v92, v1, v1
	v_fma_f32 v93, v93, v1, v1
	v_fma_f32 v94, v94, v1, v1
	v_fma_f32 v95, v95, v1, v1
	v_rcp_f32_e32 v92, v92
	v_rcp_f32_e32 v93, v93
	v_rcp_f32_e32 v94, v94
	v_rcp_f32_e32 v95, v95
	v_mul_f32_e32 v96, v96, v92
	v_mul_f32_e32 v97, v97, v93
	v_mul_f32_e32 v98, v98, v94
	v_mul_f32_e32 v99, v99, v95
	v_mul_f32_e32 v88, v84, v88
	v_mul_f32_e32 v89, v85, v89
	v_mul_f32_e32 v90, v86, v90
	v_mul_f32_e32 v91, v87, v91
	v_mul_f32_e32 v84, v0, v84
; __device__ __forceinline__ float siluf_(float x) { return x * sigmoidf_(x); }
; __device__ __forceinline__ u32x2 pack4(float a, float b, float c, float d) { return u32x2{cvtpk(a, b), cvtpk(c, d)}; }
; __device__ __forceinline__ u32x2 pack4(const f32x4& v) { return u32x2{cvtpk(v[0], v[1]), cvtpk(v[2], v[3])}; }
; #define SBAR() __builtin_amdgcn_sched_barrier(0)
; __global__ void __launch_bounds__(512) fwd_megakernel(Params p) {
;     ...
;         #pragma unroll
;         for (int ai = 0; ai < 2; ++ai)
;           #pragma unroll
;           for (int m = 0; m < 4; ++m) { SBAR();
;             int row = brow + ai * 128 + wr * 64 + m * 16 + fr;
;             const float rs = xl[ai * 128 + wr * 64 + m * 16 + fr];
;             bf16* ad = p_act + (long)row * DFF + pn * 128 + wc * 32 + fq * 4;
;             #pragma unroll
;             for (int n = 0; n < 2; ++n) {
;               float a[4];
;               #pragma unroll
;               for (int j = 0; j < 4; ++j) { float g = acc[ai][0][m][n][j] * rs, u = acc[ai][1][m][n][j] * rs; a[j] = siluf_(g) * u; }
;               *reinterpret_cast<u32x2*>(ad + n * 16) = pack4(a[0], a[1], a[2], a[3]);
;             }
	v_mul_f32_e32 v85, v0, v85
	v_mul_f32_e32 v86, v0, v86
	v_mul_f32_e32 v87, v0, v87
	v_exp_f32_e32 v84, v84
	v_exp_f32_e32 v85, v85
	v_exp_f32_e32 v86, v86
	v_exp_f32_e32 v87, v87
	v_fma_f32 v84, v84, v1, v1
	v_fma_f32 v85, v85, v1, v1
	v_fma_f32 v86, v86, v1, v1
	v_fma_f32 v87, v87, v1, v1
	v_rcp_f32_e32 v84, v84
	v_rcp_f32_e32 v85, v85
	v_rcp_f32_e32 v86, v86
	v_rcp_f32_e32 v87, v87
	v_mul_f32_e32 v88, v88, v84
	v_mul_f32_e32 v89, v89, v85
	v_mul_f32_e32 v90, v90, v86
	v_mul_f32_e32 v91, v91, v87
	v_cvt_pk_bf16_f32 v92, v96, v97
	v_cvt_pk_bf16_f32 v93, v98, v99
	v_cvt_pk_bf16_f32 v94, v88, v89
	v_cvt_pk_bf16_f32 v95, v90, v91
	s_nop 1
	v_permlane16_swap_b32_e32 v92, v94
	v_permlane16_swap_b32_e32 v93, v95
	global_store_dwordx4 v[2:3], v[92:95], off
	v_lshl_add_u64 v[134:135], v[2:3], 0, s[30:31]
	v_mul_f32_e32 v1, v139, v139
	v_mul_f32_e32 v0, 0xbfb8aa3b, v139
	v_rcp_f32_e32 v1, v1
	v_mul_f32_e32 v80, v76, v80
	v_mul_f32_e32 v81, v77, v81
	v_mul_f32_e32 v82, v78, v82
	v_mul_f32_e32 v83, v79, v83
	v_mul_f32_e32 v76, v0, v76
	v_mul_f32_e32 v77, v0, v77
	v_mul_f32_e32 v78, v0, v78
	v_mul_f32_e32 v79, v0, v79
	v_exp_f32_e32 v76, v76
	v_exp_f32_e32 v77, v77
	v_exp_f32_e32 v78, v78
	v_exp_f32_e32 v79, v79
	v_fma_f32 v76, v76, v1, v1
	v_fma_f32 v77, v77, v1, v1
	v_fma_f32 v78, v78, v1, v1
	v_fma_f32 v79, v79, v1, v1
	v_rcp_f32_e32 v76, v76
	v_rcp_f32_e32 v77, v77
	v_rcp_f32_e32 v78, v78
	v_rcp_f32_e32 v79, v79
	v_mul_f32_e32 v80, v80, v76
	v_mul_f32_e32 v81, v81, v77
	v_mul_f32_e32 v82, v82, v78
	v_mul_f32_e32 v83, v83, v79
	v_mul_f32_e32 v72, v64, v72
	v_mul_f32_e32 v73, v65, v73
	v_mul_f32_e32 v74, v66, v74
	v_mul_f32_e32 v75, v67, v75
	v_mul_f32_e32 v64, v0, v64
	v_mul_f32_e32 v65, v0, v65
	v_mul_f32_e32 v66, v0, v66
	v_mul_f32_e32 v67, v0, v67
	v_exp_f32_e32 v64, v64
	v_exp_f32_e32 v65, v65
	v_exp_f32_e32 v66, v66
	v_exp_f32_e32 v67, v67
	v_fma_f32 v64, v64, v1, v1
	v_fma_f32 v65, v65, v1, v1
	v_fma_f32 v66, v66, v1, v1
	v_fma_f32 v67, v67, v1, v1
	v_rcp_f32_e32 v64, v64
	v_rcp_f32_e32 v65, v65
	v_rcp_f32_e32 v66, v66
	v_rcp_f32_e32 v67, v67
	v_mul_f32_e32 v72, v72, v64
	v_mul_f32_e32 v73, v73, v65
	v_mul_f32_e32 v74, v74, v66
	v_mul_f32_e32 v75, v75, v67
	v_cvt_pk_bf16_f32 v76, v80, v81
	v_cvt_pk_bf16_f32 v77, v82, v83
	v_cvt_pk_bf16_f32 v78, v72, v73
	v_cvt_pk_bf16_f32 v79, v74, v75
	s_nop 1
	v_permlane16_swap_b32_e32 v76, v78
	v_permlane16_swap_b32_e32 v77, v79
	global_store_dwordx4 v[134:135], v[76:79], off
	s_mov_b32 s30, 0x6e000
	v_lshl_add_u64 v[2:3], v[134:135], 0, s[30:31]
	v_mul_f32_e32 v1, v142, v142
	v_mul_f32_e32 v0, 0xbfb8aa3b, v142
	v_rcp_f32_e32 v1, v1
	v_mul_f32_e32 v68, v60, v68
	v_mul_f32_e32 v69, v61, v69
	v_mul_f32_e32 v70, v62, v70
	v_mul_f32_e32 v71, v63, v71
	v_mul_f32_e32 v60, v0, v60
	v_mul_f32_e32 v61, v0, v61
	v_mul_f32_e32 v62, v0, v62
	v_mul_f32_e32 v63, v0, v63
	v_exp_f32_e32 v60, v60
	v_exp_f32_e32 v61, v61
	v_exp_f32_e32 v62, v62
	v_exp_f32_e32 v63, v63
	v_fma_f32 v60, v60, v1, v1
	v_fma_f32 v61, v61, v1, v1
	v_fma_f32 v62, v62, v1, v1
	v_fma_f32 v63, v63, v1, v1
	v_rcp_f32_e32 v60, v60
	v_rcp_f32_e32 v61, v61
	v_rcp_f32_e32 v62, v62
	v_rcp_f32_e32 v63, v63
	v_mul_f32_e32 v68, v68, v60
	v_mul_f32_e32 v69, v69, v61
	v_mul_f32_e32 v70, v70, v62
	v_mul_f32_e32 v71, v71, v63
	v_mul_f32_e32 v56, v52, v56
	v_mul_f32_e32 v57, v53, v57
	v_mul_f32_e32 v58, v54, v58
	v_mul_f32_e32 v59, v55, v59
	v_mul_f32_e32 v52, v0, v52
	v_mul_f32_e32 v53, v0, v53
	v_mul_f32_e32 v54, v0, v54
	v_mul_f32_e32 v55, v0, v55
	v_exp_f32_e32 v52, v52
	v_exp_f32_e32 v53, v53
	v_exp_f32_e32 v54, v54
	v_exp_f32_e32 v55, v55
	v_fma_f32 v52, v52, v1, v1
	v_fma_f32 v53, v53, v1, v1
	v_fma_f32 v54, v54, v1, v1
	v_fma_f32 v55, v55, v1, v1
	v_rcp_f32_e32 v52, v52
	v_rcp_f32_e32 v53, v53
	v_rcp_f32_e32 v54, v54
	v_rcp_f32_e32 v55, v55
	v_mul_f32_e32 v56, v56, v52
	v_mul_f32_e32 v57, v57, v53
	v_mul_f32_e32 v58, v58, v54
	v_mul_f32_e32 v59, v59, v55
	v_cvt_pk_bf16_f32 v60, v68, v69
	v_cvt_pk_bf16_f32 v61, v70, v71
	v_cvt_pk_bf16_f32 v62, v56, v57
	v_cvt_pk_bf16_f32 v63, v58, v59
	s_nop 1
	v_permlane16_swap_b32_e32 v60, v62
	v_permlane16_swap_b32_e32 v61, v63
	global_store_dwordx4 v[2:3], v[60:63], off
	s_mov_b32 s30, 0x16000
	v_lshl_add_u64 v[134:135], v[2:3], 0, s[30:31]
	v_mul_f32_e32 v1, v143, v143
	v_mul_f32_e32 v0, 0xbfb8aa3b, v143
	v_rcp_f32_e32 v1, v1
	v_mul_f32_e32 v48, v44, v48
	v_mul_f32_e32 v49, v45, v49
	v_mul_f32_e32 v50, v46, v50
	v_mul_f32_e32 v51, v47, v51
	v_mul_f32_e32 v44, v0, v44
	v_mul_f32_e32 v45, v0, v45
	v_mul_f32_e32 v46, v0, v46
	v_mul_f32_e32 v47, v0, v47
	v_exp_f32_e32 v44, v44
	v_exp_f32_e32 v45, v45
	v_exp_f32_e32 v46, v46
	v_exp_f32_e32 v47, v47
; __device__ __forceinline__ float siluf_(float x) { return x * sigmoidf_(x); }
; __device__ __forceinline__ u32x2 pack4(float a, float b, float c, float d) { return u32x2{cvtpk(a, b), cvtpk(c, d)}; }
; __device__ __forceinline__ u32x2 pack4(const f32x4& v) { return u32x2{cvtpk(v[0], v[1]), cvtpk(v[2], v[3])}; }
; #define SBAR() __builtin_amdgcn_sched_barrier(0)
; __global__ void __launch_bounds__(512) fwd_megakernel(Params p) {
;     ...
;         #pragma unroll
;         for (int ai = 0; ai < 2; ++ai)
;           #pragma unroll
;           for (int m = 0; m < 4; ++m) { SBAR();
;             int row = brow + ai * 128 + wr * 64 + m * 16 + fr;
;             const float rs = xl[ai * 128 + wr * 64 + m * 16 + fr];
;             bf16* ad = p_act + (long)row * DFF + pn * 128 + wc * 32 + fq * 4;
;             #pragma unroll
;             for (int n = 0; n < 2; ++n) {
;               float a[4];
;               #pragma unroll
;               for (int j = 0; j < 4; ++j) { float g = acc[ai][0][m][n][j] * rs, u = acc[ai][1][m][n][j] * rs; a[j] = siluf_(g) * u; }
;               *reinterpret_cast<u32x2*>(ad + n * 16) = pack4(a[0], a[1], a[2], a[3]);
;             }
	v_fma_f32 v44, v44, v1, v1
	v_fma_f32 v45, v45, v1, v1
	v_fma_f32 v46, v46, v1, v1
	v_fma_f32 v47, v47, v1, v1
	v_rcp_f32_e32 v44, v44
	v_rcp_f32_e32 v45, v45
	v_rcp_f32_e32 v46, v46
	v_rcp_f32_e32 v47, v47
	v_mul_f32_e32 v48, v48, v44
	v_mul_f32_e32 v49, v49, v45
	v_mul_f32_e32 v50, v50, v46
	v_mul_f32_e32 v51, v51, v47
	v_mul_f32_e32 v40, v36, v40
	v_mul_f32_e32 v41, v37, v41
	v_mul_f32_e32 v42, v38, v42
	v_mul_f32_e32 v43, v39, v43
	v_mul_f32_e32 v36, v0, v36
	v_mul_f32_e32 v37, v0, v37
	v_mul_f32_e32 v38, v0, v38
	v_mul_f32_e32 v39, v0, v39
	v_exp_f32_e32 v36, v36
	v_exp_f32_e32 v37, v37
	v_exp_f32_e32 v38, v38
	v_exp_f32_e32 v39, v39
	v_fma_f32 v36, v36, v1, v1
	v_fma_f32 v37, v37, v1, v1
	v_fma_f32 v38, v38, v1, v1
	v_fma_f32 v39, v39, v1, v1
	v_rcp_f32_e32 v36, v36
	v_rcp_f32_e32 v37, v37
	v_rcp_f32_e32 v38, v38
	v_rcp_f32_e32 v39, v39
	v_mul_f32_e32 v40, v40, v36
	v_mul_f32_e32 v41, v41, v37
	v_mul_f32_e32 v42, v42, v38
	v_mul_f32_e32 v43, v43, v39
	v_cvt_pk_bf16_f32 v44, v48, v49
	v_cvt_pk_bf16_f32 v45, v50, v51
	v_cvt_pk_bf16_f32 v46, v40, v41
	v_cvt_pk_bf16_f32 v47, v42, v43
	s_nop 1
	v_permlane16_swap_b32_e32 v44, v46
	v_permlane16_swap_b32_e32 v45, v47
	global_store_dwordx4 v[134:135], v[44:47], off
	v_lshl_add_u64 v[2:3], v[134:135], 0, s[30:31]
	v_mul_f32_e32 v1, v145, v145
	v_mul_f32_e32 v0, 0xbfb8aa3b, v145
	v_rcp_f32_e32 v1, v1
	v_mul_f32_e32 v32, v28, v32
	v_mul_f32_e32 v33, v29, v33
	v_mul_f32_e32 v34, v30, v34
	v_mul_f32_e32 v35, v31, v35
	v_mul_f32_e32 v28, v0, v28
	v_mul_f32_e32 v29, v0, v29
	v_mul_f32_e32 v30, v0, v30
	v_mul_f32_e32 v31, v0, v31
	v_exp_f32_e32 v28, v28
	v_exp_f32_e32 v29, v29
	v_exp_f32_e32 v30, v30
	v_exp_f32_e32 v31, v31
	v_fma_f32 v28, v28, v1, v1
	v_fma_f32 v29, v29, v1, v1
	v_fma_f32 v30, v30, v1, v1
	v_fma_f32 v31, v31, v1, v1
	v_rcp_f32_e32 v28, v28
	v_rcp_f32_e32 v29, v29
	v_rcp_f32_e32 v30, v30
	v_rcp_f32_e32 v31, v31
	v_mul_f32_e32 v32, v32, v28
	v_mul_f32_e32 v33, v33, v29
	v_mul_f32_e32 v34, v34, v30
	v_mul_f32_e32 v35, v35, v31
	v_mul_f32_e32 v24, v20, v24
	v_mul_f32_e32 v25, v21, v25
	v_mul_f32_e32 v26, v22, v26
	v_mul_f32_e32 v27, v23, v27
	v_mul_f32_e32 v20, v0, v20
	v_mul_f32_e32 v21, v0, v21
	v_mul_f32_e32 v22, v0, v22
	v_mul_f32_e32 v23, v0, v23
	v_exp_f32_e32 v20, v20
	v_exp_f32_e32 v21, v21
	v_exp_f32_e32 v22, v22
	v_exp_f32_e32 v23, v23
	v_fma_f32 v20, v20, v1, v1
	v_fma_f32 v21, v21, v1, v1
	v_fma_f32 v22, v22, v1, v1
	v_fma_f32 v23, v23, v1, v1
	v_rcp_f32_e32 v20, v20
	v_rcp_f32_e32 v21, v21
	v_rcp_f32_e32 v22, v22
	v_rcp_f32_e32 v23, v23
	v_mul_f32_e32 v24, v24, v20
	v_mul_f32_e32 v25, v25, v21
	v_mul_f32_e32 v26, v26, v22
	v_mul_f32_e32 v27, v27, v23
	v_cvt_pk_bf16_f32 v28, v32, v33
	v_cvt_pk_bf16_f32 v29, v34, v35
	v_cvt_pk_bf16_f32 v30, v24, v25
	v_cvt_pk_bf16_f32 v31, v26, v27
	s_nop 1
	v_permlane16_swap_b32_e32 v28, v30
	v_permlane16_swap_b32_e32 v29, v31
	global_store_dwordx4 v[2:3], v[28:31], off
	v_lshl_add_u64 v[134:135], v[2:3], 0, s[30:31]
	v_mul_f32_e32 v1, v132, v132
	v_mul_f32_e32 v0, 0xbfb8aa3b, v132
	v_rcp_f32_e32 v1, v1
	v_mul_f32_e32 v16, v12, v16
	v_mul_f32_e32 v17, v13, v17
	v_mul_f32_e32 v18, v14, v18
	v_mul_f32_e32 v19, v15, v19
	v_mul_f32_e32 v12, v0, v12
	v_mul_f32_e32 v13, v0, v13
	v_mul_f32_e32 v14, v0, v14
	v_mul_f32_e32 v15, v0, v15
	v_exp_f32_e32 v12, v12
	v_exp_f32_e32 v13, v13
	v_exp_f32_e32 v14, v14
	v_exp_f32_e32 v15, v15
	v_fma_f32 v12, v12, v1, v1
	v_fma_f32 v13, v13, v1, v1
	v_fma_f32 v14, v14, v1, v1
	v_fma_f32 v15, v15, v1, v1
	v_rcp_f32_e32 v12, v12
	v_rcp_f32_e32 v13, v13
	v_rcp_f32_e32 v14, v14
	v_rcp_f32_e32 v15, v15
	v_mul_f32_e32 v16, v16, v12
	v_mul_f32_e32 v17, v17, v13
	v_mul_f32_e32 v18, v18, v14
	v_mul_f32_e32 v19, v19, v15
	v_mul_f32_e32 v8, v4, v8
	v_mul_f32_e32 v9, v5, v9
	v_mul_f32_e32 v10, v6, v10
	v_mul_f32_e32 v11, v7, v11
	v_mul_f32_e32 v4, v0, v4
	v_mul_f32_e32 v5, v0, v5
	v_mul_f32_e32 v6, v0, v6
	v_mul_f32_e32 v7, v0, v7
	v_exp_f32_e32 v4, v4
	v_exp_f32_e32 v5, v5
	v_exp_f32_e32 v6, v6
	v_exp_f32_e32 v7, v7
	v_fma_f32 v4, v4, v1, v1
	v_fma_f32 v5, v5, v1, v1
	v_fma_f32 v6, v6, v1, v1
	v_fma_f32 v7, v7, v1, v1
	v_rcp_f32_e32 v4, v4
	v_rcp_f32_e32 v5, v5
	v_rcp_f32_e32 v6, v6
	v_rcp_f32_e32 v7, v7
	v_mul_f32_e32 v8, v8, v4
	v_mul_f32_e32 v9, v9, v5
	v_mul_f32_e32 v10, v10, v6
	v_mul_f32_e32 v11, v11, v7
	v_cvt_pk_bf16_f32 v12, v16, v17
	v_cvt_pk_bf16_f32 v13, v18, v19
	v_cvt_pk_bf16_f32 v14, v8, v9
	v_cvt_pk_bf16_f32 v15, v10, v11
	s_nop 1
	v_permlane16_swap_b32_e32 v12, v14
	v_permlane16_swap_b32_e32 v13, v15
	global_store_dwordx4 v[134:135], v[12:15], off
	s_mov_b32 s4, s62
	s_and_b64 vcc, exec, s[28:29]
	s_cbranch_vccnz .LBB0_689
